# G3 row-scale table: one unit per wave (four rows per lane, all partial-sum loads in flight) so the unit order is evaluated once per wave instead of three times
# speedup vs baseline: 1.0088x; 1.0088x over previous
.LBB0_141:
	s_andn2_b64 vcc, exec, s[4:5]
	s_cbranch_vccnz .LBB0_352
	v_readlane_b32 s2, v254, 36
	s_add_u32 s30, s2, s16
	v_readlane_b32 s2, v254, 39
	v_ashrrev_i32_e32 v2, 6, v170
	s_addc_u32 s31, s2, s17
	v_cmp_gt_i32_e32 vcc, 8, v2
	s_and_saveexec_b64 s[38:39], vcc
	v_readlane_b32 s0, v254, 40
	s_mov_b64 s[80:81], 0x200
	v_readlane_b32 s1, v254, 41
	s_cmp_gt_i32 s22, 63
	s_cselect_b64 s[98:99], -1, 0
	s_and_b64 s[98:99], s[98:99], s[0:1]
	s_and_b64 vcc, exec, s[98:99]
	s_cbranch_vccnz .Lhoist_g3a_skip
	v_readlane_b32 s84, v254, 31
	v_readlane_b32 s82, v254, 37
	v_readlane_b32 s83, v254, 38
	s_mul_i32 s84, s84, 0xb00000
	s_add_u32 s84, s82, s84
	s_addc_u32 s85, s83, 0
	s_add_u32 s84, s84, 0x2100000
	s_addc_u32 s85, s85, 0
	s_mov_b32 s76, s72
	s_ashr_i32 s77, s72, 31
	s_lshl_b64 s[76:77], s[76:77], 19
	s_add_u32 s84, s84, s76
	s_addc_u32 s85, s85, s77
	s_mov_b32 s76, s22
	s_ashr_i32 s77, s22, 31
	s_lshl_b64 s[76:77], s[76:77], 19
	s_add_u32 s82, s48, s76
	s_addc_u32 s83, s49, s77
	s_ashr_i32 s86, s29, 6
	s_lshl_b32 s86, s86, 10
	s_add_i32 m0, s86, 0x10000
	s_nop 0
	global_load_lds_dwordx4 v164, s[84:85]
	s_add_i32 m0, s86, 0x12000
	s_nop 0
	global_load_lds_dwordx4 v174, s[84:85]
	s_add_u32 s76, s84, 0x40000
	s_addc_u32 s77, s85, 0
	s_add_i32 m0, s86, 0x14000
	s_nop 0
	global_load_lds_dwordx4 v164, s[76:77]
	s_add_i32 m0, s86, 0x16000
	s_nop 0
	global_load_lds_dwordx4 v174, s[76:77]
	s_mov_b32 m0, s86
	s_nop 0
	global_load_lds_dwordx4 v162, s[82:83]
	s_add_i32 m0, s86, 0x2000
	s_nop 0
	global_load_lds_dwordx4 v172, s[82:83]
	s_add_u32 s76, s82, 0x40000
	s_addc_u32 s77, s83, 0
	s_add_i32 m0, s86, 0x4000
	s_nop 0
	global_load_lds_dwordx4 v162, s[76:77]
	s_add_i32 m0, s86, 0x6000
	s_nop 0
	global_load_lds_dwordx4 v172, s[76:77]
.Lhoist_g3a_skip:
	s_cbranch_execz .LBB0_229
	s_lshr_b32 s21, s10, 3
	s_ashr_i32 s91, s90, 31
	s_ashr_i32 s59, s94, 31
	s_and_b32 s23, s10, 4
	s_add_i32 s26, s21, 1
	s_cmpk_gt_i32 s94, 0x7f
	s_cselect_b64 s[40:41], -1, 0
	s_cmpk_gt_u32 s94, 0x97
	s_cselect_b64 s[42:43], -1, 0
	s_cmpk_gt_u32 s94, 0xc3
	s_cselect_b64 s[44:45], -1, 0
	s_cmpk_gt_u32 s94, 0xf7
	s_cselect_b64 s[50:51], -1, 0
	s_cmpk_lt_u32 s94, 0xcc
	s_cselect_b64 s[52:53], -1, 0
	s_cmpk_lt_u32 s94, 0xf4
	s_movk_i32 s2, 0xffd0
	s_cselect_b32 s2, s2, 0xffffffa4
	s_add_i32 s4, s2, s94
	s_add_i32 s16, s4, 0x400
	s_and_b32 s4, s4, 7
	v_mov_b32_e32 v0, s23
	v_sub_co_u32_e32 v3, vcc, s4, v0
	s_nop 0
	v_readfirstlane_b32 s5, v3
	s_mul_i32 s27, s26, s23
	s_mul_i32 s5, s5, s21
	s_lshr_b32 s62, s16, 3
	s_add_i32 s63, s27, s5
	s_mul_i32 s64, s26, s4
	s_add_i32 s4, s94, 0x134
	s_cmp_lt_i32 s4, s10
	s_cselect_b64 s[54:55], -1, 0
	s_and_b32 s6, s4, 7
	v_sub_co_u32_e64 v3, s[4:5], s6, v0
	s_nop 0
	v_readfirstlane_b32 s7, v3
	s_mul_i32 s7, s7, s21
	s_add_i32 s65, s27, s7
	s_mul_i32 s66, s26, s6
	s_add_i32 s6, s94, 0xffffff52
	s_cmp_lt_u32 s6, 0xffffffea
	s_mov_b32 s11, s17
	s_cselect_b32 s71, 0x41, 64
	s_add_i32 s6, s94, 0xffffff80
	v_mov_b64_e32 v[4:5], s[10:11]
	s_lshr_b32 s6, s6, 3
	v_cmp_ge_u64_e64 s[2:3], s[16:17], v[4:5]
	s_add_i32 s16, s6, 2
	s_lshl_b64 s[6:7], s[16:17], 8
	s_add_u32 s6, s6, s94
	s_addc_u32 s9, s7, 0
	s_or_b32 s8, s6, 0xf8
	v_cmp_ge_u64_e64 s[6:7], s[8:9], v[4:5]
	s_lshr_b32 s74, s8, 3
	v_sub_co_u32_e64 v0, s[8:9], s70, v0
	s_nop 0
	v_readfirstlane_b32 s16, v0
	s_mul_i32 s16, s16, s21
	s_add_i32 s67, s27, s16
	s_and_b64 s[60:61], vcc, exec
	s_cselect_b32 s16, s64, s63
	s_add_i32 s16, s16, s62
	s_and_b64 s[4:5], s[4:5], exec
	s_cselect_b32 s73, s66, s65
	s_add_i32 s73, s73, 63
	s_mov_b64 s[78:79], s[68:69]
	s_mul_i32 s68, s26, s70
	v_and_b32_e32 v0, 63, v170
	s_and_b64 s[4:5], s[8:9], exec
	s_cselect_b32 s4, s68, s67
	v_lshlrev_b32_e32 v8, 2, v0
	s_mov_b32 s58, s94
	s_add_i32 s74, s74, s4
	v_lshl_or_b32 v8, v2, 10, v8
	v_readlane_b32 s4, v254, 19
	v_ashrrev_i32_e32 v3, 31, v2
	s_mov_b32 s95, s17
	v_add_u32_e32 v12, s4, v8
	v_mov_b64_e32 v[8:9], s[58:59]
	v_lshlrev_b64 v[6:7], 8, v[2:3]
	v_mad_i64_i32 v[8:9], s[4:5], s90, v2, v[8:9]
	s_mov_b64 s[68:69], s[78:79]
	v_lshl_add_u64 v[4:5], v[6:7], 0, s[94:95]
	v_lshl_add_u64 v[6:7], v[6:7], 0, s[58:59]
	s_lshl_b64 s[4:5], s[90:91], 1
	s_mov_b64 s[8:9], 0
	s_xor_b64 s[6:7], s[6:7], -1
	s_branch .LBB0_148

.LBB0_146:
	s_or_b64 exec, exec, s[60:61]
	v_lshl_add_u64 v[2:3], v[2:3], 0, 2
	ds_write_b32 v12, v10
	ds_write_b32 v12, v30 offset:256
	ds_write_b32 v12, v31 offset:512
	ds_write_b32 v12, v32 offset:768
	v_add_u32_e32 v10, -2, v2
	v_cmp_lt_i32_e32 vcc, -1, v10
	v_lshl_add_u64 v[4:5], v[4:5], 0, s[80:81]
	v_lshl_add_u64 v[6:7], v[6:7], 0, s[80:81]
	v_add_u32_e32 v12, 0x800, v12
	v_lshl_add_u64 v[8:9], v[8:9], 0, s[4:5]
	s_orn2_b64 s[62:63], vcc, exec

.LBB0_195:
	v_cmp_gt_i32_e32 vcc, 64, v13
	v_mov_b32_e32 v10, 0
	v_mov_b32_e32 v30, 0
	v_mov_b32_e32 v31, 0
	v_mov_b32_e32 v32, 0
	s_and_saveexec_b64 s[60:61], vcc
	s_cbranch_execz .LBB0_146
	v_lshl_or_b32 v33, v13, 8, v0
	v_lshlrev_b32_e32 v33, 2, v33
	s_mov_b64 s[98:99], s[30:31]
	global_load_dword v34, v33, s[98:99]
	global_load_dword v50, v33, s[98:99] offset:256
	global_load_dword v66, v33, s[98:99] offset:512
	global_load_dword v82, v33, s[98:99] offset:768
	s_add_u32 s98, s98, 0x10800
	s_addc_u32 s99, s99, 0
	global_load_dword v35, v33, s[98:99]
	global_load_dword v51, v33, s[98:99] offset:256
	global_load_dword v67, v33, s[98:99] offset:512
	global_load_dword v83, v33, s[98:99] offset:768
	s_add_u32 s98, s98, 0x10800
	s_addc_u32 s99, s99, 0
	global_load_dword v36, v33, s[98:99]
	global_load_dword v52, v33, s[98:99] offset:256
	global_load_dword v68, v33, s[98:99] offset:512
	global_load_dword v84, v33, s[98:99] offset:768
	s_add_u32 s98, s98, 0x10800
	s_addc_u32 s99, s99, 0
	global_load_dword v37, v33, s[98:99]
	global_load_dword v53, v33, s[98:99] offset:256
	global_load_dword v69, v33, s[98:99] offset:512
	global_load_dword v85, v33, s[98:99] offset:768
	s_add_u32 s98, s98, 0x10800
	s_addc_u32 s99, s99, 0
	global_load_dword v38, v33, s[98:99]
	global_load_dword v54, v33, s[98:99] offset:256
	global_load_dword v70, v33, s[98:99] offset:512
	global_load_dword v86, v33, s[98:99] offset:768
	s_add_u32 s98, s98, 0x10800
	s_addc_u32 s99, s99, 0
	global_load_dword v39, v33, s[98:99]
	global_load_dword v55, v33, s[98:99] offset:256
	global_load_dword v71, v33, s[98:99] offset:512
	global_load_dword v87, v33, s[98:99] offset:768
	s_add_u32 s98, s98, 0x10800
	s_addc_u32 s99, s99, 0
	global_load_dword v40, v33, s[98:99]
	global_load_dword v56, v33, s[98:99] offset:256
	global_load_dword v72, v33, s[98:99] offset:512
	global_load_dword v88, v33, s[98:99] offset:768
	s_add_u32 s98, s98, 0x10800
	s_addc_u32 s99, s99, 0
	global_load_dword v41, v33, s[98:99]
	global_load_dword v57, v33, s[98:99] offset:256
	global_load_dword v73, v33, s[98:99] offset:512
	global_load_dword v89, v33, s[98:99] offset:768
	s_add_u32 s98, s98, 0x10800
	s_addc_u32 s99, s99, 0
	global_load_dword v42, v33, s[98:99]
	global_load_dword v58, v33, s[98:99] offset:256
	global_load_dword v74, v33, s[98:99] offset:512
	global_load_dword v90, v33, s[98:99] offset:768
	s_add_u32 s98, s98, 0x10800
	s_addc_u32 s99, s99, 0
	global_load_dword v43, v33, s[98:99]
	global_load_dword v59, v33, s[98:99] offset:256
	global_load_dword v75, v33, s[98:99] offset:512
	global_load_dword v91, v33, s[98:99] offset:768
	s_add_u32 s98, s98, 0x10800
	s_addc_u32 s99, s99, 0
	global_load_dword v44, v33, s[98:99]
	global_load_dword v60, v33, s[98:99] offset:256
	global_load_dword v76, v33, s[98:99] offset:512
	global_load_dword v92, v33, s[98:99] offset:768
	s_add_u32 s98, s98, 0x10800
	s_addc_u32 s99, s99, 0
	global_load_dword v45, v33, s[98:99]
	global_load_dword v61, v33, s[98:99] offset:256
	global_load_dword v77, v33, s[98:99] offset:512
	global_load_dword v93, v33, s[98:99] offset:768
	s_add_u32 s98, s98, 0x10800
	s_addc_u32 s99, s99, 0
	global_load_dword v46, v33, s[98:99]
	global_load_dword v62, v33, s[98:99] offset:256
	global_load_dword v78, v33, s[98:99] offset:512
	global_load_dword v94, v33, s[98:99] offset:768
	s_add_u32 s98, s98, 0x10800
	s_addc_u32 s99, s99, 0
	global_load_dword v47, v33, s[98:99]
	global_load_dword v63, v33, s[98:99] offset:256
	global_load_dword v79, v33, s[98:99] offset:512
	global_load_dword v95, v33, s[98:99] offset:768
	s_add_u32 s98, s98, 0x10800
	s_addc_u32 s99, s99, 0
	global_load_dword v48, v33, s[98:99]
	global_load_dword v64, v33, s[98:99] offset:256
	global_load_dword v80, v33, s[98:99] offset:512
	global_load_dword v96, v33, s[98:99] offset:768
	s_add_u32 s98, s98, 0x10800
	s_addc_u32 s99, s99, 0
	global_load_dword v49, v33, s[98:99]
	global_load_dword v65, v33, s[98:99] offset:256
	global_load_dword v81, v33, s[98:99] offset:512
	global_load_dword v97, v33, s[98:99] offset:768
	s_waitcnt vmcnt(0)
	v_add_f32_e32 v10, v34, v35
	v_add_f32_e32 v30, v50, v51
	v_add_f32_e32 v31, v66, v67
	v_add_f32_e32 v32, v82, v83
	v_add_f32_e32 v10, v10, v36
	v_add_f32_e32 v30, v30, v52
	v_add_f32_e32 v31, v31, v68
	v_add_f32_e32 v32, v32, v84
	v_add_f32_e32 v10, v10, v37
	v_add_f32_e32 v30, v30, v53
	v_add_f32_e32 v31, v31, v69
	v_add_f32_e32 v32, v32, v85
	v_add_f32_e32 v10, v10, v38
	v_add_f32_e32 v30, v30, v54
	v_add_f32_e32 v31, v31, v70
	v_add_f32_e32 v32, v32, v86
	v_add_f32_e32 v10, v10, v39
	v_add_f32_e32 v30, v30, v55
	v_add_f32_e32 v31, v31, v71
	v_add_f32_e32 v32, v32, v87
	v_add_f32_e32 v10, v10, v40
	v_add_f32_e32 v30, v30, v56
	v_add_f32_e32 v31, v31, v72
	v_add_f32_e32 v32, v32, v88
	v_add_f32_e32 v10, v10, v41
	v_add_f32_e32 v30, v30, v57
	v_add_f32_e32 v31, v31, v73
	v_add_f32_e32 v32, v32, v89
	v_add_f32_e32 v10, v10, v42
	v_add_f32_e32 v30, v30, v58
	v_add_f32_e32 v31, v31, v74
	v_add_f32_e32 v32, v32, v90
	v_add_f32_e32 v10, v10, v43
	v_add_f32_e32 v30, v30, v59
	v_add_f32_e32 v31, v31, v75
	v_add_f32_e32 v32, v32, v91
	v_add_f32_e32 v10, v10, v44
	v_add_f32_e32 v30, v30, v60
	v_add_f32_e32 v31, v31, v76
	v_add_f32_e32 v32, v32, v92
	v_add_f32_e32 v10, v10, v45
	v_add_f32_e32 v30, v30, v61
	v_add_f32_e32 v31, v31, v77
	v_add_f32_e32 v32, v32, v93
	v_add_f32_e32 v10, v10, v46
	v_add_f32_e32 v30, v30, v62
	v_add_f32_e32 v31, v31, v78
	v_add_f32_e32 v32, v32, v94
	v_add_f32_e32 v10, v10, v47
	v_add_f32_e32 v30, v30, v63
	v_add_f32_e32 v31, v31, v79
	v_add_f32_e32 v32, v32, v95
	v_add_f32_e32 v10, v10, v48
	v_add_f32_e32 v30, v30, v64
	v_add_f32_e32 v31, v31, v80
	v_add_f32_e32 v32, v32, v96
	v_add_f32_e32 v10, v10, v49
	v_add_f32_e32 v30, v30, v65
	v_add_f32_e32 v31, v31, v81
	v_add_f32_e32 v32, v32, v97
	v_fmamk_f32 v10, v10, 0x3a800000, v208
	v_fmamk_f32 v30, v30, 0x3a800000, v208
	v_fmamk_f32 v31, v31, 0x3a800000, v208
	v_fmamk_f32 v32, v32, 0x3a800000, v208
	v_rsq_f32_e32 v10, v10
	v_rsq_f32_e32 v30, v30
	v_rsq_f32_e32 v31, v31
	v_rsq_f32_e32 v32, v32
	s_branch .LBB0_146
